# convert_w w1/w3/w2: each wave converts 4 consecutive k-groups of one 64-column block so every lane writes a contiguous 64-B piece; all loads in flight
# speedup vs baseline: 1.0068x; 1.0020x over previous
; DI int TID() { int t = threadIdx.x; asm volatile("" : "+v"(t)); return t; }
; DI int BID() { int t = blockIdx.x; asm volatile("" : "+s"(t)); return t; }
; DI unsigned pk2(float a, float b) { f32x2_t v = {a, b}; bf16x2_t r = __builtin_convertvector(v, bf16x2_t); return __builtin_bit_cast(unsigned, r); }
; DI void convert_w(const float* src, const float* src2, int srcN, int K, bf16_t* dst, int Nd, int mode) {
;   const size_t gsz = (size_t)gridDim.x * NTHR, gid = (size_t)BID() * NTHR + TID();
;   const size_t total = (size_t)Nd * (K >> 3);
;   for (size_t e = gid; e < total; e += gsz) {
;     int nd = (int)(e % Nd), k0 = (int)(e / Nd) * 8;
;     const float* s = src; int col = nd; bool valid = true;
;     if (mode == 0) { valid = nd < srcN; }
;     else if (mode == 1) { int g = nd >> 6, w = nd & 63; if (w < 32) col = g * 32 + w; else { s = src2; col = g * 32 + w - 32; } }
;     else { if (nd < 1024) col = (nd >> 7) * 192 + (nd & 127); else { int r = nd - 1024; col = (r >> 6) * 192 + 128 + (r & 63); } }
;     float v[8];
; #pragma unroll
;     for (int j = 0; j < 8; ++j) v[j] = valid ? s[(size_t)(k0 + j) * srcN + col] : 0.f;
;     uint4 o; o.x = pk2(v[0], v[1]); o.y = pk2(v[2], v[3]); o.z = pk2(v[4], v[5]); o.w = pk2(v[6], v[7]);
;     *(uint4*)(dst + (size_t)nd * K + k0) = o;
;   }
.LBB0_945:
	s_lshr_b32 s30, s34, 6
	s_cmpk_lg_u32 s30, 0x800
	s_cbranch_scc1 .Lcv1_old
	v_lshrrev_b32_e32 v2, 6, v167
	v_and_b32_e32 v3, 63, v167
	s_lshl_b32 s25, s50, 3
	v_and_b32_e32 v4, 31, v3
	v_readfirstlane_b32 s24, v2
	v_cmp_gt_u32_e32 vcc, 32, v3
	v_mov_b32_e32 v5, s57
	v_mov_b32_e32 v6, s59
	v_mov_b32_e32 v7, s56
	v_mov_b32_e32 v8, s58
	s_add_u32 s25, s24, s25
	v_cndmask_b32_e32 v11, v6, v5, vcc
	v_cndmask_b32_e32 v10, v8, v7, vcc
	v_lshl_add_u64 v[10:11], v[10:11], 0, s[0:1]
	v_lshlrev_b32_e32 v140, 2, v4
	v_lshl_add_u64 v[10:11], v[10:11], 0, v[140:141]
	s_mov_b64 s[36:37], 0x2c00
	v_lshl_add_u64 v[12:13], v[10:11], 0, s[36:37]
	s_mov_b64 s[36:37], 0x5800
	v_lshl_add_u64 v[14:15], v[10:11], 0, s[36:37]
	s_mov_b64 s[36:37], 0x8400
	v_lshl_add_u64 v[16:17], v[10:11], 0, s[36:37]
	s_mov_b64 s[36:37], 0xb000
	v_lshl_add_u64 v[18:19], v[10:11], 0, s[36:37]
	s_mov_b64 s[36:37], 0xdc00
	v_lshl_add_u64 v[20:21], v[10:11], 0, s[36:37]
	s_mov_b64 s[36:37], 0x10800
	v_lshl_add_u64 v[22:23], v[10:11], 0, s[36:37]
	s_mov_b64 s[36:37], 0x13400
	v_lshl_add_u64 v[24:25], v[10:11], 0, s[36:37]
	v_lshlrev_b32_e32 v140, 11, v3
	v_lshl_add_u64 v[28:29], s[20:21], 0, v[140:141]
	s_mov_b32 s39, 0
	s_cmpk_lt_u32 s25, 0x300
	s_cbranch_scc0 .Lcv1_n5
	s_mov_b32 s31, s25
	s_mul_hi_u32 s36, s31, 0x2e8ba2f
	s_mul_i32 s37, s36, 0x58
	s_sub_u32 s37, s31, s37
	s_mul_i32 s38, s36, 0x58000
	s_lshl_b32 s3, s37, 7
	s_add_u32 s38, s38, s3
	s_lshl_b32 s3, s37, 17
	s_lshl_b32 s24, s36, 6
	s_add_u32 s3, s3, s24
	v_mov_b32_e32 v104, s3
	v_lshl_add_u64 v[30:31], v[10:11], 0, s[38:39]
	global_load_dword v40, v[30:31], off
	v_lshl_add_u64 v[32:33], v[12:13], 0, s[38:39]
	global_load_dword v41, v[32:33], off
	v_lshl_add_u64 v[30:31], v[14:15], 0, s[38:39]
	global_load_dword v42, v[30:31], off
	v_lshl_add_u64 v[32:33], v[16:17], 0, s[38:39]
	global_load_dword v43, v[32:33], off
	v_lshl_add_u64 v[30:31], v[18:19], 0, s[38:39]
	global_load_dword v44, v[30:31], off
	v_lshl_add_u64 v[32:33], v[20:21], 0, s[38:39]
	global_load_dword v45, v[32:33], off
	v_lshl_add_u64 v[30:31], v[22:23], 0, s[38:39]
	global_load_dword v46, v[30:31], off
	v_lshl_add_u64 v[32:33], v[24:25], 0, s[38:39]
	global_load_dword v47, v[32:33], off
	s_add_u32 s38, s38, 0x16000
	s_add_u32 s3, s3, 16
	v_mov_b32_e32 v105, s3
	v_lshl_add_u64 v[30:31], v[10:11], 0, s[38:39]
	global_load_dword v48, v[30:31], off
	v_lshl_add_u64 v[32:33], v[12:13], 0, s[38:39]
	global_load_dword v49, v[32:33], off
	v_lshl_add_u64 v[30:31], v[14:15], 0, s[38:39]
	global_load_dword v50, v[30:31], off
	v_lshl_add_u64 v[32:33], v[16:17], 0, s[38:39]
	global_load_dword v51, v[32:33], off
	v_lshl_add_u64 v[30:31], v[18:19], 0, s[38:39]
	global_load_dword v52, v[30:31], off
	v_lshl_add_u64 v[32:33], v[20:21], 0, s[38:39]
	global_load_dword v53, v[32:33], off
	v_lshl_add_u64 v[30:31], v[22:23], 0, s[38:39]
	global_load_dword v54, v[30:31], off
	v_lshl_add_u64 v[32:33], v[24:25], 0, s[38:39]
	global_load_dword v55, v[32:33], off
	s_add_u32 s38, s38, 0x16000
	s_add_u32 s3, s3, 16
	v_mov_b32_e32 v106, s3
	v_lshl_add_u64 v[30:31], v[10:11], 0, s[38:39]
	global_load_dword v56, v[30:31], off
	v_lshl_add_u64 v[32:33], v[12:13], 0, s[38:39]
	global_load_dword v57, v[32:33], off
	v_lshl_add_u64 v[30:31], v[14:15], 0, s[38:39]
	global_load_dword v58, v[30:31], off
	v_lshl_add_u64 v[32:33], v[16:17], 0, s[38:39]
	global_load_dword v59, v[32:33], off
	v_lshl_add_u64 v[30:31], v[18:19], 0, s[38:39]
	global_load_dword v60, v[30:31], off
	v_lshl_add_u64 v[32:33], v[20:21], 0, s[38:39]
	global_load_dword v61, v[32:33], off
	v_lshl_add_u64 v[30:31], v[22:23], 0, s[38:39]
	global_load_dword v62, v[30:31], off
	v_lshl_add_u64 v[32:33], v[24:25], 0, s[38:39]
	global_load_dword v63, v[32:33], off
	s_add_u32 s38, s38, 0x16000
	s_add_u32 s3, s3, 16
	v_mov_b32_e32 v107, s3
	v_lshl_add_u64 v[30:31], v[10:11], 0, s[38:39]
	global_load_dword v64, v[30:31], off
	v_lshl_add_u64 v[32:33], v[12:13], 0, s[38:39]
	global_load_dword v65, v[32:33], off
	v_lshl_add_u64 v[30:31], v[14:15], 0, s[38:39]
	global_load_dword v66, v[30:31], off
	v_lshl_add_u64 v[32:33], v[16:17], 0, s[38:39]
	global_load_dword v67, v[32:33], off
	v_lshl_add_u64 v[30:31], v[18:19], 0, s[38:39]
	global_load_dword v68, v[30:31], off
	v_lshl_add_u64 v[32:33], v[20:21], 0, s[38:39]
	global_load_dword v69, v[32:33], off
	v_lshl_add_u64 v[30:31], v[22:23], 0, s[38:39]
	global_load_dword v70, v[30:31], off
	v_lshl_add_u64 v[32:33], v[24:25], 0, s[38:39]
	global_load_dword v71, v[32:33], off
	s_add_u32 s31, s31, s30
	s_mul_hi_u32 s36, s31, 0x2e8ba2f
	s_mul_i32 s37, s36, 0x58
	s_sub_u32 s37, s31, s37
	s_mul_i32 s38, s36, 0x58000
	s_lshl_b32 s3, s37, 7
	s_add_u32 s38, s38, s3
	s_lshl_b32 s3, s37, 17
	s_lshl_b32 s24, s36, 6
	s_add_u32 s3, s3, s24
	v_mov_b32_e32 v108, s3
	v_lshl_add_u64 v[30:31], v[10:11], 0, s[38:39]
	global_load_dword v72, v[30:31], off
	v_lshl_add_u64 v[32:33], v[12:13], 0, s[38:39]
	global_load_dword v73, v[32:33], off
	v_lshl_add_u64 v[30:31], v[14:15], 0, s[38:39]
	global_load_dword v74, v[30:31], off
	v_lshl_add_u64 v[32:33], v[16:17], 0, s[38:39]
	global_load_dword v75, v[32:33], off
	v_lshl_add_u64 v[30:31], v[18:19], 0, s[38:39]
	global_load_dword v76, v[30:31], off
	v_lshl_add_u64 v[32:33], v[20:21], 0, s[38:39]
	global_load_dword v77, v[32:33], off
	v_lshl_add_u64 v[30:31], v[22:23], 0, s[38:39]
	global_load_dword v78, v[30:31], off
	v_lshl_add_u64 v[32:33], v[24:25], 0, s[38:39]
	global_load_dword v79, v[32:33], off
	s_add_u32 s38, s38, 0x16000
	s_add_u32 s3, s3, 16
	v_mov_b32_e32 v109, s3
	v_lshl_add_u64 v[30:31], v[10:11], 0, s[38:39]
	global_load_dword v80, v[30:31], off
; DI unsigned pk2(float a, float b) { f32x2_t v = {a, b}; bf16x2_t r = __builtin_convertvector(v, bf16x2_t); return __builtin_bit_cast(unsigned, r); }
; DI void convert_w(const float* src, const float* src2, int srcN, int K, bf16_t* dst, int Nd, int mode) {
;     ...
;   for (size_t e = gid; e < total; e += gsz) {
;     int nd = (int)(e % Nd), k0 = (int)(e / Nd) * 8;
;     const float* s = src; int col = nd; bool valid = true;
;     if (mode == 0) { valid = nd < srcN; }
;     else if (mode == 1) { int g = nd >> 6, w = nd & 63; if (w < 32) col = g * 32 + w; else { s = src2; col = g * 32 + w - 32; } }
;     else { if (nd < 1024) col = (nd >> 7) * 192 + (nd & 127); else { int r = nd - 1024; col = (r >> 6) * 192 + 128 + (r & 63); } }
;     float v[8];
; #pragma unroll
;     for (int j = 0; j < 8; ++j) v[j] = valid ? s[(size_t)(k0 + j) * srcN + col] : 0.f;
;     uint4 o; o.x = pk2(v[0], v[1]); o.y = pk2(v[2], v[3]); o.z = pk2(v[4], v[5]); o.w = pk2(v[6], v[7]);
;     *(uint4*)(dst + (size_t)nd * K + k0) = o;
;   }
	v_lshl_add_u64 v[32:33], v[12:13], 0, s[38:39]
	global_load_dword v81, v[32:33], off
	v_lshl_add_u64 v[30:31], v[14:15], 0, s[38:39]
	global_load_dword v82, v[30:31], off
	v_lshl_add_u64 v[32:33], v[16:17], 0, s[38:39]
	global_load_dword v83, v[32:33], off
	v_lshl_add_u64 v[30:31], v[18:19], 0, s[38:39]
	global_load_dword v84, v[30:31], off
	v_lshl_add_u64 v[32:33], v[20:21], 0, s[38:39]
	global_load_dword v85, v[32:33], off
	v_lshl_add_u64 v[30:31], v[22:23], 0, s[38:39]
	global_load_dword v86, v[30:31], off
	v_lshl_add_u64 v[32:33], v[24:25], 0, s[38:39]
	global_load_dword v87, v[32:33], off
	s_add_u32 s38, s38, 0x16000
	s_add_u32 s3, s3, 16
	v_mov_b32_e32 v110, s3
	v_lshl_add_u64 v[30:31], v[10:11], 0, s[38:39]
	global_load_dword v88, v[30:31], off
	v_lshl_add_u64 v[32:33], v[12:13], 0, s[38:39]
	global_load_dword v89, v[32:33], off
	v_lshl_add_u64 v[30:31], v[14:15], 0, s[38:39]
	global_load_dword v90, v[30:31], off
	v_lshl_add_u64 v[32:33], v[16:17], 0, s[38:39]
	global_load_dword v91, v[32:33], off
	v_lshl_add_u64 v[30:31], v[18:19], 0, s[38:39]
	global_load_dword v92, v[30:31], off
	v_lshl_add_u64 v[32:33], v[20:21], 0, s[38:39]
	global_load_dword v93, v[32:33], off
	v_lshl_add_u64 v[30:31], v[22:23], 0, s[38:39]
	global_load_dword v94, v[30:31], off
	v_lshl_add_u64 v[32:33], v[24:25], 0, s[38:39]
	global_load_dword v95, v[32:33], off
	s_add_u32 s38, s38, 0x16000
	s_add_u32 s3, s3, 16
	v_mov_b32_e32 v111, s3
	v_lshl_add_u64 v[30:31], v[10:11], 0, s[38:39]
	global_load_dword v96, v[30:31], off
	v_lshl_add_u64 v[32:33], v[12:13], 0, s[38:39]
	global_load_dword v97, v[32:33], off
	v_lshl_add_u64 v[30:31], v[14:15], 0, s[38:39]
	global_load_dword v98, v[30:31], off
	v_lshl_add_u64 v[32:33], v[16:17], 0, s[38:39]
	global_load_dword v99, v[32:33], off
	v_lshl_add_u64 v[30:31], v[18:19], 0, s[38:39]
	global_load_dword v100, v[30:31], off
	v_lshl_add_u64 v[32:33], v[20:21], 0, s[38:39]
	global_load_dword v101, v[32:33], off
	v_lshl_add_u64 v[30:31], v[22:23], 0, s[38:39]
	global_load_dword v102, v[30:31], off
	v_lshl_add_u64 v[32:33], v[24:25], 0, s[38:39]
	global_load_dword v103, v[32:33], off
	s_waitcnt vmcnt(56)
	v_cvt_pk_bf16_f32 v40, v40, v41
	v_cvt_pk_bf16_f32 v41, v42, v43
	v_cvt_pk_bf16_f32 v42, v44, v45
	v_cvt_pk_bf16_f32 v43, v46, v47
	v_mov_b32_e32 v140, v104
	v_lshl_add_u64 v[34:35], v[28:29], 0, v[140:141]
	global_store_dwordx4 v[34:35], v[40:43], off
	s_waitcnt vmcnt(49)
	v_cvt_pk_bf16_f32 v48, v48, v49
	v_cvt_pk_bf16_f32 v49, v50, v51
	v_cvt_pk_bf16_f32 v50, v52, v53
	v_cvt_pk_bf16_f32 v51, v54, v55
	v_mov_b32_e32 v140, v105
	v_lshl_add_u64 v[34:35], v[28:29], 0, v[140:141]
	global_store_dwordx4 v[34:35], v[48:51], off
	s_waitcnt vmcnt(42)
	v_cvt_pk_bf16_f32 v56, v56, v57
	v_cvt_pk_bf16_f32 v57, v58, v59
	v_cvt_pk_bf16_f32 v58, v60, v61
	v_cvt_pk_bf16_f32 v59, v62, v63
	v_mov_b32_e32 v140, v106
	v_lshl_add_u64 v[34:35], v[28:29], 0, v[140:141]
	global_store_dwordx4 v[34:35], v[56:59], off
	s_waitcnt vmcnt(35)
	v_cvt_pk_bf16_f32 v64, v64, v65
	v_cvt_pk_bf16_f32 v65, v66, v67
	v_cvt_pk_bf16_f32 v66, v68, v69
	v_cvt_pk_bf16_f32 v67, v70, v71
	v_mov_b32_e32 v140, v107
	v_lshl_add_u64 v[34:35], v[28:29], 0, v[140:141]
	global_store_dwordx4 v[34:35], v[64:67], off
	s_waitcnt vmcnt(28)
	v_cvt_pk_bf16_f32 v72, v72, v73
	v_cvt_pk_bf16_f32 v73, v74, v75
	v_cvt_pk_bf16_f32 v74, v76, v77
	v_cvt_pk_bf16_f32 v75, v78, v79
	v_mov_b32_e32 v140, v108
	v_lshl_add_u64 v[34:35], v[28:29], 0, v[140:141]
	global_store_dwordx4 v[34:35], v[72:75], off
	s_waitcnt vmcnt(21)
	v_cvt_pk_bf16_f32 v80, v80, v81
	v_cvt_pk_bf16_f32 v81, v82, v83
	v_cvt_pk_bf16_f32 v82, v84, v85
	v_cvt_pk_bf16_f32 v83, v86, v87
	v_mov_b32_e32 v140, v109
	v_lshl_add_u64 v[34:35], v[28:29], 0, v[140:141]
	global_store_dwordx4 v[34:35], v[80:83], off
	s_waitcnt vmcnt(14)
	v_cvt_pk_bf16_f32 v88, v88, v89
	v_cvt_pk_bf16_f32 v89, v90, v91
	v_cvt_pk_bf16_f32 v90, v92, v93
	v_cvt_pk_bf16_f32 v91, v94, v95
	v_mov_b32_e32 v140, v110
	v_lshl_add_u64 v[34:35], v[28:29], 0, v[140:141]
	global_store_dwordx4 v[34:35], v[88:91], off
	s_waitcnt vmcnt(7)
	v_cvt_pk_bf16_f32 v96, v96, v97
	v_cvt_pk_bf16_f32 v97, v98, v99
	v_cvt_pk_bf16_f32 v98, v100, v101
	v_cvt_pk_bf16_f32 v99, v102, v103
	v_mov_b32_e32 v140, v111
	v_lshl_add_u64 v[34:35], v[28:29], 0, v[140:141]
	global_store_dwordx4 v[34:35], v[96:99], off
	s_branch .LBB0_946
; DI unsigned pk2(float a, float b) { f32x2_t v = {a, b}; bf16x2_t r = __builtin_convertvector(v, bf16x2_t); return __builtin_bit_cast(unsigned, r); }
; DI void convert_w(const float* src, const float* src2, int srcN, int K, bf16_t* dst, int Nd, int mode) {
;     ...
;   for (size_t e = gid; e < total; e += gsz) {
;     int nd = (int)(e % Nd), k0 = (int)(e / Nd) * 8;
;     const float* s = src; int col = nd; bool valid = true;
;     if (mode == 0) { valid = nd < srcN; }
;     else if (mode == 1) { int g = nd >> 6, w = nd & 63; if (w < 32) col = g * 32 + w; else { s = src2; col = g * 32 + w - 32; } }
;     else { if (nd < 1024) col = (nd >> 7) * 192 + (nd & 127); else { int r = nd - 1024; col = (r >> 6) * 192 + 128 + (r & 63); } }
;     float v[8];
; #pragma unroll
;     for (int j = 0; j < 8; ++j) v[j] = valid ? s[(size_t)(k0 + j) * srcN + col] : 0.f;
;     uint4 o; o.x = pk2(v[0], v[1]); o.y = pk2(v[2], v[3]); o.z = pk2(v[4], v[5]); o.w = pk2(v[6], v[7]);
;     *(uint4*)(dst + (size_t)nd * K + k0) = o;
;   }
.Lcv1_n5:
	s_mov_b32 s31, s25
	s_mul_hi_u32 s36, s31, 0x2e8ba2f
	s_mul_i32 s37, s36, 0x58
	s_sub_u32 s37, s31, s37
	s_mul_i32 s38, s36, 0x58000
	s_lshl_b32 s3, s37, 7
	s_add_u32 s38, s38, s3
	s_lshl_b32 s3, s37, 17
	s_lshl_b32 s24, s36, 6
	s_add_u32 s3, s3, s24
	v_mov_b32_e32 v104, s3
	v_lshl_add_u64 v[30:31], v[10:11], 0, s[38:39]
	global_load_dword v40, v[30:31], off
	v_lshl_add_u64 v[32:33], v[12:13], 0, s[38:39]
	global_load_dword v41, v[32:33], off
	v_lshl_add_u64 v[30:31], v[14:15], 0, s[38:39]
	global_load_dword v42, v[30:31], off
	v_lshl_add_u64 v[32:33], v[16:17], 0, s[38:39]
	global_load_dword v43, v[32:33], off
	v_lshl_add_u64 v[30:31], v[18:19], 0, s[38:39]
	global_load_dword v44, v[30:31], off
	v_lshl_add_u64 v[32:33], v[20:21], 0, s[38:39]
	global_load_dword v45, v[32:33], off
	v_lshl_add_u64 v[30:31], v[22:23], 0, s[38:39]
	global_load_dword v46, v[30:31], off
	v_lshl_add_u64 v[32:33], v[24:25], 0, s[38:39]
	global_load_dword v47, v[32:33], off
	s_add_u32 s38, s38, 0x16000
	s_add_u32 s3, s3, 16
	v_mov_b32_e32 v105, s3
	v_lshl_add_u64 v[30:31], v[10:11], 0, s[38:39]
	global_load_dword v48, v[30:31], off
	v_lshl_add_u64 v[32:33], v[12:13], 0, s[38:39]
	global_load_dword v49, v[32:33], off
	v_lshl_add_u64 v[30:31], v[14:15], 0, s[38:39]
	global_load_dword v50, v[30:31], off
	v_lshl_add_u64 v[32:33], v[16:17], 0, s[38:39]
	global_load_dword v51, v[32:33], off
	v_lshl_add_u64 v[30:31], v[18:19], 0, s[38:39]
	global_load_dword v52, v[30:31], off
	v_lshl_add_u64 v[32:33], v[20:21], 0, s[38:39]
	global_load_dword v53, v[32:33], off
	v_lshl_add_u64 v[30:31], v[22:23], 0, s[38:39]
	global_load_dword v54, v[30:31], off
	v_lshl_add_u64 v[32:33], v[24:25], 0, s[38:39]
	global_load_dword v55, v[32:33], off
	s_add_u32 s38, s38, 0x16000
	s_add_u32 s3, s3, 16
	v_mov_b32_e32 v106, s3
	v_lshl_add_u64 v[30:31], v[10:11], 0, s[38:39]
	global_load_dword v56, v[30:31], off
	v_lshl_add_u64 v[32:33], v[12:13], 0, s[38:39]
	global_load_dword v57, v[32:33], off
	v_lshl_add_u64 v[30:31], v[14:15], 0, s[38:39]
	global_load_dword v58, v[30:31], off
	v_lshl_add_u64 v[32:33], v[16:17], 0, s[38:39]
	global_load_dword v59, v[32:33], off
	v_lshl_add_u64 v[30:31], v[18:19], 0, s[38:39]
	global_load_dword v60, v[30:31], off
	v_lshl_add_u64 v[32:33], v[20:21], 0, s[38:39]
	global_load_dword v61, v[32:33], off
	v_lshl_add_u64 v[30:31], v[22:23], 0, s[38:39]
	global_load_dword v62, v[30:31], off
	v_lshl_add_u64 v[32:33], v[24:25], 0, s[38:39]
	global_load_dword v63, v[32:33], off
	s_add_u32 s38, s38, 0x16000
	s_add_u32 s3, s3, 16
	v_mov_b32_e32 v107, s3
	v_lshl_add_u64 v[30:31], v[10:11], 0, s[38:39]
	global_load_dword v64, v[30:31], off
	v_lshl_add_u64 v[32:33], v[12:13], 0, s[38:39]
	global_load_dword v65, v[32:33], off
	v_lshl_add_u64 v[30:31], v[14:15], 0, s[38:39]
	global_load_dword v66, v[30:31], off
	v_lshl_add_u64 v[32:33], v[16:17], 0, s[38:39]
	global_load_dword v67, v[32:33], off
	v_lshl_add_u64 v[30:31], v[18:19], 0, s[38:39]
	global_load_dword v68, v[30:31], off
	v_lshl_add_u64 v[32:33], v[20:21], 0, s[38:39]
	global_load_dword v69, v[32:33], off
	v_lshl_add_u64 v[30:31], v[22:23], 0, s[38:39]
	global_load_dword v70, v[30:31], off
	v_lshl_add_u64 v[32:33], v[24:25], 0, s[38:39]
	global_load_dword v71, v[32:33], off
	s_waitcnt vmcnt(24)
	v_cvt_pk_bf16_f32 v40, v40, v41
	v_cvt_pk_bf16_f32 v41, v42, v43
	v_cvt_pk_bf16_f32 v42, v44, v45
	v_cvt_pk_bf16_f32 v43, v46, v47
	v_mov_b32_e32 v140, v104
	v_lshl_add_u64 v[34:35], v[28:29], 0, v[140:141]
	global_store_dwordx4 v[34:35], v[40:43], off
	s_waitcnt vmcnt(17)
	v_cvt_pk_bf16_f32 v48, v48, v49
	v_cvt_pk_bf16_f32 v49, v50, v51
	v_cvt_pk_bf16_f32 v50, v52, v53
	v_cvt_pk_bf16_f32 v51, v54, v55
	v_mov_b32_e32 v140, v105
	v_lshl_add_u64 v[34:35], v[28:29], 0, v[140:141]
	global_store_dwordx4 v[34:35], v[48:51], off
	s_waitcnt vmcnt(10)
	v_cvt_pk_bf16_f32 v56, v56, v57
	v_cvt_pk_bf16_f32 v57, v58, v59
	v_cvt_pk_bf16_f32 v58, v60, v61
	v_cvt_pk_bf16_f32 v59, v62, v63
	v_mov_b32_e32 v140, v106
	v_lshl_add_u64 v[34:35], v[28:29], 0, v[140:141]
	global_store_dwordx4 v[34:35], v[56:59], off
	s_waitcnt vmcnt(3)
	v_cvt_pk_bf16_f32 v64, v64, v65
	v_cvt_pk_bf16_f32 v65, v66, v67
	v_cvt_pk_bf16_f32 v66, v68, v69
	v_cvt_pk_bf16_f32 v67, v70, v71
	v_mov_b32_e32 v140, v107
	v_lshl_add_u64 v[34:35], v[28:29], 0, v[140:141]
	global_store_dwordx4 v[34:35], v[64:67], off
	s_branch .LBB0_946

; DI int TID() { int t = threadIdx.x; asm volatile("" : "+v"(t)); return t; }
; DI int BID() { int t = blockIdx.x; asm volatile("" : "+s"(t)); return t; }
; DI unsigned pk2(float a, float b) { f32x2_t v = {a, b}; bf16x2_t r = __builtin_convertvector(v, bf16x2_t); return __builtin_bit_cast(unsigned, r); }
; DI void convert_w(const float* src, const float* src2, int srcN, int K, bf16_t* dst, int Nd, int mode) {
;   const size_t gsz = (size_t)gridDim.x * NTHR, gid = (size_t)BID() * NTHR + TID();
;   const size_t total = (size_t)Nd * (K >> 3);
;   for (size_t e = gid; e < total; e += gsz) {
;     int nd = (int)(e % Nd), k0 = (int)(e / Nd) * 8;
;     const float* s = src; int col = nd; bool valid = true;
;     if (mode == 0) { valid = nd < srcN; }
;     else if (mode == 1) { int g = nd >> 6, w = nd & 63; if (w < 32) col = g * 32 + w; else { s = src2; col = g * 32 + w - 32; } }
;     else { if (nd < 1024) col = (nd >> 7) * 192 + (nd & 127); else { int r = nd - 1024; col = (r >> 6) * 192 + 128 + (r & 63); } }
;     float v[8];
; #pragma unroll
;     for (int j = 0; j < 8; ++j) v[j] = valid ? s[(size_t)(k0 + j) * srcN + col] : 0.f;
;     uint4 o; o.x = pk2(v[0], v[1]); o.y = pk2(v[2], v[3]); o.z = pk2(v[4], v[5]); o.w = pk2(v[6], v[7]);
;     *(uint4*)(dst + (size_t)nd * K + k0) = o;
;   }
.LBB0_948:
	s_lshr_b32 s30, s36, 6
	s_cmpk_lg_u32 s30, 0x800
	s_cbranch_scc1 .Lcv2_old
	v_lshrrev_b32_e32 v2, 6, v167
	v_and_b32_e32 v3, 63, v167
	s_lshl_b32 s25, s50, 3
	v_lshlrev_b32_e32 v140, 2, v3
	v_readfirstlane_b32 s24, v2
	v_lshl_add_u64 v[10:11], s[0:1], 0, v[140:141]
	s_nop 1
	s_add_u32 s25, s24, s25
	s_mov_b64 s[38:39], 0x1000
	v_lshl_add_u64 v[12:13], v[10:11], 0, s[38:39]
	s_mov_b64 s[38:39], 0x2000
	v_lshl_add_u64 v[14:15], v[10:11], 0, s[38:39]
	s_mov_b64 s[38:39], 0x3000
	v_lshl_add_u64 v[16:17], v[10:11], 0, s[38:39]
	s_mov_b64 s[38:39], 0x4000
	v_lshl_add_u64 v[18:19], v[10:11], 0, s[38:39]
	s_mov_b64 s[38:39], 0x5000
	v_lshl_add_u64 v[20:21], v[10:11], 0, s[38:39]
	s_mov_b64 s[38:39], 0x6000
	v_lshl_add_u64 v[22:23], v[10:11], 0, s[38:39]
	s_mov_b64 s[38:39], 0x7000
	v_lshl_add_u64 v[24:25], v[10:11], 0, s[38:39]
	v_mul_u32_u24_e32 v140, 0x1600, v3
	v_lshl_add_u64 v[28:29], s[34:35], 0, v[140:141]
	s_mov_b32 s39, 0
	s_cmpk_lt_u32 s25, 0x580
	s_cbranch_scc0 .LBB0_949
	s_mov_b32 s31, s25
	s_lshr_b32 s24, s31, 4
	s_and_b32 s38, s31, 15
	s_mul_i32 s3, s38, 0x58000
	s_lshl_b32 s38, s38, 8
	s_lshl_b32 s37, s24, 6
	s_add_u32 s3, s3, s37
	s_lshl_b32 s37, s24, 17
	s_add_u32 s38, s38, s37
	s_mov_b32 s37, 0
	v_mov_b32_e32 v104, s3
	v_lshl_add_u64 v[30:31], v[10:11], 0, s[38:39]
	global_load_dword v40, v[30:31], off
	v_lshl_add_u64 v[32:33], v[12:13], 0, s[38:39]
	global_load_dword v41, v[32:33], off
	v_lshl_add_u64 v[30:31], v[14:15], 0, s[38:39]
	global_load_dword v42, v[30:31], off
	v_lshl_add_u64 v[32:33], v[16:17], 0, s[38:39]
	global_load_dword v43, v[32:33], off
	v_lshl_add_u64 v[30:31], v[18:19], 0, s[38:39]
	global_load_dword v44, v[30:31], off
	v_lshl_add_u64 v[32:33], v[20:21], 0, s[38:39]
	global_load_dword v45, v[32:33], off
	v_lshl_add_u64 v[30:31], v[22:23], 0, s[38:39]
	global_load_dword v46, v[30:31], off
	v_lshl_add_u64 v[32:33], v[24:25], 0, s[38:39]
	global_load_dword v47, v[32:33], off
	s_add_u32 s38, s38, 0x8000
	s_add_u32 s3, s3, 16
	v_mov_b32_e32 v105, s3
	v_lshl_add_u64 v[30:31], v[10:11], 0, s[38:39]
	global_load_dword v48, v[30:31], off
	v_lshl_add_u64 v[32:33], v[12:13], 0, s[38:39]
	global_load_dword v49, v[32:33], off
	v_lshl_add_u64 v[30:31], v[14:15], 0, s[38:39]
	global_load_dword v50, v[30:31], off
	v_lshl_add_u64 v[32:33], v[16:17], 0, s[38:39]
	global_load_dword v51, v[32:33], off
	v_lshl_add_u64 v[30:31], v[18:19], 0, s[38:39]
	global_load_dword v52, v[30:31], off
	v_lshl_add_u64 v[32:33], v[20:21], 0, s[38:39]
	global_load_dword v53, v[32:33], off
	v_lshl_add_u64 v[30:31], v[22:23], 0, s[38:39]
	global_load_dword v54, v[30:31], off
	v_lshl_add_u64 v[32:33], v[24:25], 0, s[38:39]
	global_load_dword v55, v[32:33], off
	s_add_u32 s38, s38, 0x8000
	s_add_u32 s3, s3, 16
	v_mov_b32_e32 v106, s3
	v_lshl_add_u64 v[30:31], v[10:11], 0, s[38:39]
	global_load_dword v56, v[30:31], off
	v_lshl_add_u64 v[32:33], v[12:13], 0, s[38:39]
	global_load_dword v57, v[32:33], off
	v_lshl_add_u64 v[30:31], v[14:15], 0, s[38:39]
	global_load_dword v58, v[30:31], off
	v_lshl_add_u64 v[32:33], v[16:17], 0, s[38:39]
	global_load_dword v59, v[32:33], off
	v_lshl_add_u64 v[30:31], v[18:19], 0, s[38:39]
	global_load_dword v60, v[30:31], off
	v_lshl_add_u64 v[32:33], v[20:21], 0, s[38:39]
	global_load_dword v61, v[32:33], off
	v_lshl_add_u64 v[30:31], v[22:23], 0, s[38:39]
	global_load_dword v62, v[30:31], off
	v_lshl_add_u64 v[32:33], v[24:25], 0, s[38:39]
	global_load_dword v63, v[32:33], off
	s_add_u32 s38, s38, 0x8000
	s_add_u32 s3, s3, 16
	v_mov_b32_e32 v107, s3
	v_lshl_add_u64 v[30:31], v[10:11], 0, s[38:39]
	global_load_dword v64, v[30:31], off
	v_lshl_add_u64 v[32:33], v[12:13], 0, s[38:39]
	global_load_dword v65, v[32:33], off
	v_lshl_add_u64 v[30:31], v[14:15], 0, s[38:39]
	global_load_dword v66, v[30:31], off
	v_lshl_add_u64 v[32:33], v[16:17], 0, s[38:39]
	global_load_dword v67, v[32:33], off
	v_lshl_add_u64 v[30:31], v[18:19], 0, s[38:39]
	global_load_dword v68, v[30:31], off
	v_lshl_add_u64 v[32:33], v[20:21], 0, s[38:39]
	global_load_dword v69, v[32:33], off
	v_lshl_add_u64 v[30:31], v[22:23], 0, s[38:39]
	global_load_dword v70, v[30:31], off
	v_lshl_add_u64 v[32:33], v[24:25], 0, s[38:39]
	global_load_dword v71, v[32:33], off
	s_waitcnt vmcnt(24)
	v_cvt_pk_bf16_f32 v40, v40, v41
	v_cvt_pk_bf16_f32 v41, v42, v43
	v_cvt_pk_bf16_f32 v42, v44, v45
	v_cvt_pk_bf16_f32 v43, v46, v47
	v_mov_b32_e32 v140, v104
	v_lshl_add_u64 v[34:35], v[28:29], 0, v[140:141]
	global_store_dwordx4 v[34:35], v[40:43], off
	s_waitcnt vmcnt(17)
	v_cvt_pk_bf16_f32 v48, v48, v49
	v_cvt_pk_bf16_f32 v49, v50, v51
	v_cvt_pk_bf16_f32 v50, v52, v53
	v_cvt_pk_bf16_f32 v51, v54, v55
	v_mov_b32_e32 v140, v105
	v_lshl_add_u64 v[34:35], v[28:29], 0, v[140:141]
	global_store_dwordx4 v[34:35], v[48:51], off
	s_waitcnt vmcnt(10)
	v_cvt_pk_bf16_f32 v56, v56, v57
	v_cvt_pk_bf16_f32 v57, v58, v59
	v_cvt_pk_bf16_f32 v58, v60, v61
	v_cvt_pk_bf16_f32 v59, v62, v63
	v_mov_b32_e32 v140, v106
	v_lshl_add_u64 v[34:35], v[28:29], 0, v[140:141]
	global_store_dwordx4 v[34:35], v[56:59], off
	s_waitcnt vmcnt(3)
	v_cvt_pk_bf16_f32 v64, v64, v65
	v_cvt_pk_bf16_f32 v65, v66, v67
	v_cvt_pk_bf16_f32 v66, v68, v69
	v_cvt_pk_bf16_f32 v67, v70, v71
	v_mov_b32_e32 v140, v107
	v_lshl_add_u64 v[34:35], v[28:29], 0, v[140:141]
	global_store_dwordx4 v[34:35], v[64:67], off
	s_branch .LBB0_949
